# attention unit decode: key-norm maxima read with ordinary loads instead of system-scope (sc1) loads; they were the oldest loads of the prologue so every counted wait sat behind their latency
# speedup vs baseline: 1.0003x; 1.0003x over previous
; __device__ __forceinline__ void attn_unit(const bf16* __restrict__ P, bf16* __restrict__ MIXIN, const float* __restrict__ gn, int seq0, int h, int q0, int nt, float kmax0, float kmax1, float slope, float lam, char* lds) {
;     ...
;   const int qpos = q0 + wq * 32 + r32;
;   const bf16* Qw = P + (size_t)(seq0 + qpos) * LDP + C_DAQ + h * 128 + mp * 64 + hi * 8;
; #pragma unroll
;   for (int d0 = 0; d0 < 4; ++d0) qr[d0] = *reinterpret_cast<const bf16x8*>(Qw + d0 * 16);
;   const bf16* Kh = P + (size_t)seq0 * LDP + C_DAK + h * 128;
;   int t0, t1; float m_reg;
;   { const bf16* Kw = Kh + (size_t)qpos * LDP + mp * 64 + hi * 8; float qn = 0.f, sd = 0.f;
; #pragma unroll
;     for (int d0 = 0; d0 < 4; ++d0) { const bf16x8 kf = *reinterpret_cast<const bf16x8*>(Kw + d0 * 16);
; #pragma unroll
;       for (int e = 0; e < 8; ++e) { const float qv = bf2f((unsigned short)qr[d0][e]), kv = bf2f((unsigned short)kf[e]); qn += qv * qv; sd += qv * kv; } }
; __global__ void __launch_bounds__(NWAVES * 64, 2) hymba_fwd(Args args) {
;     ...
;             const float kmax0 = sqrtf(__uint_as_float(__hip_atomic_load(ctl + CW_NORM + sq * 16 + 8 + h * 2 + 0, __ATOMIC_RELAXED, __HIP_MEMORY_SCOPE_AGENT)));
;             const float kmax1 = sqrtf(__uint_as_float(__hip_atomic_load(ctl + CW_NORM + sq * 16 + 8 + h * 2 + 1, __ATOMIC_RELAXED, __HIP_MEMORY_SCOPE_AGENT)));
.LBB0_307:
	s_sub_i32 s85, 3, s24
	s_lshl_b64 s[0:1], s[0:1], 2
	s_add_u32 s6, s70, s0
	s_addc_u32 s7, s71, s1
	s_lshl_b32 s10, s85, 1
	s_lshl_b64 s[0:1], s[10:11], 2
	s_add_u32 s0, s6, s0
	s_addc_u32 s1, s7, s1
	global_load_dword v22, v177, s[0:1] offset:544
	global_load_dword v23, v177, s[0:1] offset:548
	v_mov_b32_e32 v229, v210
	s_mul_i32 s0, s35, 0xd00
	v_ashrrev_i32_e32 v21, 6, v229
	v_lshlrev_b32_e32 v0, 5, v21
	v_and_b32_e32 v36, 31, v229
	v_and_b32_e32 v0, 0x60, v0
	s_mov_b32 s1, s11
	v_or3_b32 v20, s31, v0, v36
	s_lshl_b32 s10, s85, 8
	s_lshl_b64 s[0:1], s[0:1], 1
	v_add_u32_e32 v0, s35, v20
	s_add_u32 s0, s44, s0
	v_mul_i32_i24_e32 v176, 0xd00, v0
	v_ashrrev_i32_e32 v0, 2, v229
	s_addc_u32 s1, s45, s1
	v_and_b32_e32 v32, 0xffffffc0, v0
	s_add_u32 s24, s0, s10
	v_ashrrev_i32_e32 v33, 31, v32
	s_addc_u32 s25, s1, 0
	v_mul_u32_u24_e32 v0, 0xd00, v20
	v_mov_b32_e32 v1, v177
	v_bfe_u32 v19, v229, 5, 1
	v_lshlrev_b64 v[8:9], 1, v[32:33]
	v_lshl_add_u64 v[0:1], v[0:1], 1, s[24:25]
	v_lshl_add_u64 v[2:3], v[176:177], 1, s[44:45]
	v_lshlrev_b32_e32 v176, 4, v19
	v_lshl_add_u64 v[0:1], v[0:1], 0, v[8:9]
	v_lshl_add_u64 v[0:1], v[0:1], 0, v[176:177]
	global_load_dwordx4 v[4:7], v[0:1], off offset:1024
	v_lshl_add_u64 v[2:3], v[2:3], 0, s[10:11]
	v_lshl_add_u64 v[2:3], v[2:3], 0, v[8:9]
	v_lshl_add_u64 v[16:17], v[2:3], 0, v[176:177]
	global_load_dwordx4 v[132:135], v[16:17], off
	global_load_dwordx4 v[128:131], v[16:17], off offset:32
	global_load_dwordx4 v[8:11], v[0:1], off offset:1056
	global_load_dwordx4 v[12:15], v[0:1], off offset:1088
	s_nop 0
	global_load_dwordx4 v[0:3], v[0:1], off offset:1120
	s_nop 0
	global_load_dwordx4 v[140:143], v[16:17], off offset:64
	global_load_dwordx4 v[136:139], v[16:17], off offset:96
	s_waitcnt vmcnt(9)
	v_mul_f32_e32 v24, 0x4f800000, v22
	v_cmp_gt_f32_e32 vcc, s26, v22
	s_waitcnt vmcnt(8)
	v_mul_f32_e32 v25, 0x4f800000, v23
	v_cmp_gt_f32_e64 s[0:1], s26, v23
	v_cndmask_b32_e32 v24, v22, v24, vcc
	s_waitcnt vmcnt(6)
	v_and_b32_e32 v33, 0xffff0000, v133
	v_cndmask_b32_e64 v22, v23, v25, s[0:1]
	v_sqrt_f32_e32 v23, v24
	v_sqrt_f32_e32 v25, v22
	v_lshlrev_b32_e32 v34, 16, v134
	v_and_b32_e32 v35, 0xffff0000, v134
	v_add_u32_e32 v16, -1, v23
	v_add_u32_e32 v26, -1, v25
	v_fma_f32 v28, -v16, v23, v24
	v_add_u32_e32 v17, 1, v23
	v_fma_f32 v30, -v26, v25, v22
	v_cmp_ge_f32_e64 s[6:7], 0, v28
	v_add_u32_e32 v27, 1, v25
	v_fma_f32 v29, -v17, v23, v24
	v_cndmask_b32_e64 v16, v23, v16, s[6:7]
	v_cmp_ge_f32_e64 s[6:7], 0, v30
	v_fma_f32 v31, -v27, v25, v22
	v_and_b32_e32 v30, 0xffff0000, v132
	v_cndmask_b32_e64 v23, v25, v26, s[6:7]
	v_cmp_lt_f32_e64 s[6:7], 0, v29
	v_lshlrev_b32_e32 v26, 16, v5
	v_and_b32_e32 v25, 0xffff0000, v4
	v_cndmask_b32_e64 v16, v16, v17, s[6:7]
	v_cmp_lt_f32_e64 s[6:7], 0, v31
	v_lshlrev_b32_e32 v28, 16, v6
	v_and_b32_e32 v29, 0xffff0000, v6
	v_cndmask_b32_e64 v17, v23, v27, s[6:7]
	v_and_b32_e32 v27, 0xffff0000, v5
	v_mul_f32_e32 v5, 0x37800000, v17
	v_lshlrev_b32_e32 v23, 16, v4
	v_mul_f32_e32 v4, 0x37800000, v16
	v_cndmask_b32_e64 v5, v17, v5, s[0:1]
	v_lshlrev_b32_e32 v17, 16, v132
	v_cndmask_b32_e32 v4, v16, v4, vcc
	v_fma_f32 v6, v17, v23, 0
	v_mul_f32_e32 v16, v30, v30
	v_lshlrev_b32_e32 v31, 16, v133
	v_fmac_f32_e32 v16, v17, v17
	v_fmac_f32_e32 v6, v30, v25
	v_fmac_f32_e32 v16, v31, v31
	v_fmac_f32_e32 v6, v31, v26
	v_fmac_f32_e32 v16, v33, v33
	v_fmac_f32_e32 v6, v33, v27
	v_fmac_f32_e32 v16, v34, v34
	v_fmac_f32_e32 v6, v34, v28
	v_fmac_f32_e32 v16, v35, v35
	v_fmac_f32_e32 v6, v35, v29
	v_lshlrev_b32_e32 v17, 16, v135
	v_lshlrev_b32_e32 v23, 16, v7
	v_fmac_f32_e32 v16, v17, v17
	v_fmac_f32_e32 v6, v17, v23
	v_and_b32_e32 v17, 0xffff0000, v135
	v_and_b32_e32 v7, 0xffff0000, v7
	v_fmac_f32_e32 v16, v17, v17
	v_fmac_f32_e32 v6, v17, v7
	s_waitcnt vmcnt(5)
	v_lshlrev_b32_e32 v7, 16, v128
	s_waitcnt vmcnt(4)
	v_lshlrev_b32_e32 v17, 16, v8
	v_fmac_f32_e32 v16, v7, v7
	v_fmac_f32_e32 v6, v7, v17
	v_and_b32_e32 v7, 0xffff0000, v128
	v_and_b32_e32 v8, 0xffff0000, v8
	v_fmac_f32_e32 v16, v7, v7
	v_fmac_f32_e32 v6, v7, v8
	v_lshlrev_b32_e32 v7, 16, v129
	v_lshlrev_b32_e32 v8, 16, v9
	v_fmac_f32_e32 v16, v7, v7
	v_fmac_f32_e32 v6, v7, v8
	v_and_b32_e32 v7, 0xffff0000, v129
	v_and_b32_e32 v8, 0xffff0000, v9
	v_fmac_f32_e32 v16, v7, v7
	v_fmac_f32_e32 v6, v7, v8
	v_lshlrev_b32_e32 v7, 16, v130
	v_lshlrev_b32_e32 v8, 16, v10
	v_fmac_f32_e32 v16, v7, v7
	v_fmac_f32_e32 v6, v7, v8
	v_and_b32_e32 v7, 0xffff0000, v130
	v_and_b32_e32 v8, 0xffff0000, v10
	v_fmac_f32_e32 v16, v7, v7
	v_fmac_f32_e32 v6, v7, v8
	v_lshlrev_b32_e32 v7, 16, v131
	v_lshlrev_b32_e32 v8, 16, v11
	v_fmac_f32_e32 v16, v7, v7
	v_fmac_f32_e32 v6, v7, v8
	v_and_b32_e32 v7, 0xffff0000, v131
	v_and_b32_e32 v8, 0xffff0000, v11
	v_fmac_f32_e32 v16, v7, v7
	v_fmac_f32_e32 v6, v7, v8
	s_waitcnt vmcnt(1)
; __device__ __forceinline__ void attn_unit(const bf16* __restrict__ P, bf16* __restrict__ MIXIN, const float* __restrict__ gn, int seq0, int h, int q0, int nt, float kmax0, float kmax1, float slope, float lam, char* lds) {
;     ...
;   { const bf16* Kw = Kh + (size_t)qpos * LDP + mp * 64 + hi * 8; float qn = 0.f, sd = 0.f;
; #pragma unroll
;     for (int d0 = 0; d0 < 4; ++d0) { const bf16x8 kf = *reinterpret_cast<const bf16x8*>(Kw + d0 * 16);
; #pragma unroll
;       for (int e = 0; e < 8; ++e) { const float qv = bf2f((unsigned short)qr[d0][e]), kv = bf2f((unsigned short)kf[e]); qn += qv * qv; sd += qv * kv; } }
;     qn += __shfl_xor(qn, 32); sd += __shfl_xor(sd, 32);
;     const float ub = sqrtf(qn) * (mp ? kmax1 : kmax0) * 1.0001f;
;     m_reg = fminf(ub, sd + 60.f);
;     float bnd = ub - sd;
;     bnd = fmaxf(bnd, __shfl_xor(bnd, 1)); bnd = fmaxf(bnd, __shfl_xor(bnd, 2)); bnd = fmaxf(bnd, __shfl_xor(bnd, 4)); bnd = fmaxf(bnd, __shfl_xor(bnd, 8)); bnd = fmaxf(bnd, __shfl_xor(bnd, 16));
;     float* wsb = (float*)(lds + 2 * SHM_V + 2 * SHM_K);
;     if (lane == 0) wsb[wid] = bnd;
	v_lshlrev_b32_e32 v7, 16, v140
	v_lshlrev_b32_e32 v8, 16, v12
	v_fmac_f32_e32 v16, v7, v7
	v_fmac_f32_e32 v6, v7, v8
	v_and_b32_e32 v7, 0xffff0000, v140
	v_and_b32_e32 v8, 0xffff0000, v12
	v_fmac_f32_e32 v16, v7, v7
	v_fmac_f32_e32 v6, v7, v8
	v_lshlrev_b32_e32 v7, 16, v141
	v_lshlrev_b32_e32 v8, 16, v13
	v_fmac_f32_e32 v16, v7, v7
	v_fmac_f32_e32 v6, v7, v8
	v_and_b32_e32 v7, 0xffff0000, v141
	v_and_b32_e32 v8, 0xffff0000, v13
	v_fmac_f32_e32 v16, v7, v7
	v_fmac_f32_e32 v6, v7, v8
	v_lshlrev_b32_e32 v7, 16, v142
	v_lshlrev_b32_e32 v8, 16, v14
	v_fmac_f32_e32 v16, v7, v7
	v_fmac_f32_e32 v6, v7, v8
	v_and_b32_e32 v7, 0xffff0000, v142
	v_and_b32_e32 v8, 0xffff0000, v14
	v_fmac_f32_e32 v16, v7, v7
	v_fmac_f32_e32 v6, v7, v8
	v_lshlrev_b32_e32 v7, 16, v143
	v_lshlrev_b32_e32 v8, 16, v15
	v_fmac_f32_e32 v16, v7, v7
	v_fmac_f32_e32 v6, v7, v8
	v_and_b32_e32 v7, 0xffff0000, v143
	v_and_b32_e32 v8, 0xffff0000, v15
	v_fmac_f32_e32 v16, v7, v7
	v_fmac_f32_e32 v6, v7, v8
	s_waitcnt vmcnt(0)
	v_lshlrev_b32_e32 v7, 16, v136
	v_lshlrev_b32_e32 v8, 16, v0
	v_fmac_f32_e32 v16, v7, v7
	v_fmac_f32_e32 v6, v7, v8
	v_and_b32_e32 v7, 0xffff0000, v136
	v_and_b32_e32 v0, 0xffff0000, v0
	v_fmac_f32_e32 v16, v7, v7
	v_fmac_f32_e32 v6, v7, v0
	v_lshlrev_b32_e32 v0, 16, v137
	v_lshlrev_b32_e32 v7, 16, v1
	v_fmac_f32_e32 v16, v0, v0
	v_fmac_f32_e32 v6, v0, v7
	v_and_b32_e32 v0, 0xffff0000, v137
	v_and_b32_e32 v1, 0xffff0000, v1
	v_fmac_f32_e32 v16, v0, v0
	v_fmac_f32_e32 v6, v0, v1
	v_lshlrev_b32_e32 v0, 16, v138
	v_lshlrev_b32_e32 v1, 16, v2
	v_cmp_class_f32_e32 vcc, v24, v220
	v_fmac_f32_e32 v16, v0, v0
	v_fmac_f32_e32 v6, v0, v1
	v_and_b32_e32 v0, 0xffff0000, v138
	v_and_b32_e32 v1, 0xffff0000, v2
	v_cndmask_b32_e32 v4, v4, v24, vcc
	v_fmac_f32_e32 v16, v0, v0
	v_fmac_f32_e32 v6, v0, v1
	v_lshlrev_b32_e32 v0, 16, v139
	v_cmp_lt_i32_e32 vcc, v214, v213
	v_fmac_f32_e32 v16, v0, v0
	v_and_b32_e32 v1, 0xffff0000, v139
	v_cndmask_b32_e32 v2, v211, v214, vcc
	v_fmac_f32_e32 v16, v1, v1
	v_lshlrev_b32_e32 v2, 2, v2
	ds_bpermute_b32 v7, v2, v16
	v_lshlrev_b32_e32 v8, 16, v3
	v_fmac_f32_e32 v6, v0, v8
	v_and_b32_e32 v0, 0xffff0000, v3
	v_fmac_f32_e32 v6, v1, v0
	s_waitcnt lgkmcnt(0)
	v_add_f32_e32 v0, v16, v7
	ds_bpermute_b32 v1, v2, v6
	v_mul_f32_e32 v2, 0x4f800000, v0
	v_cmp_gt_f32_e32 vcc, s26, v0
	v_cmp_class_f32_e64 s[0:1], v22, v220
	v_and_b32_e32 v33, 63, v229
	v_cndmask_b32_e32 v2, v0, v2, vcc
	v_sqrt_f32_e32 v3, v2
	s_waitcnt lgkmcnt(0)
	v_add_f32_e32 v0, v6, v1
	v_cndmask_b32_e64 v5, v5, v22, s[0:1]
	v_add_u32_e32 v1, -1, v3
	v_fma_f32 v6, -v1, v3, v2
	v_cmp_ge_f32_e64 s[0:1], 0, v6
	v_add_u32_e32 v6, 1, v3
	s_nop 0
	v_cndmask_b32_e64 v1, v3, v1, s[0:1]
	v_fma_f32 v3, -v6, v3, v2
	v_cmp_lt_f32_e64 s[0:1], 0, v3
	s_nop 1
	v_cndmask_b32_e64 v1, v1, v6, s[0:1]
	v_mul_f32_e32 v3, 0x37800000, v1
	v_cndmask_b32_e32 v1, v1, v3, vcc
	v_cmp_class_f32_e32 vcc, v2, v220
	s_mov_b32 s0, 0x3f800347
	s_nop 0
	v_cndmask_b32_e32 v1, v1, v2, vcc
	v_cmp_gt_u32_e32 vcc, s28, v229
	s_nop 1
	v_cndmask_b32_e32 v2, v5, v4, vcc
	v_cmp_lt_i32_e32 vcc, v252, v213
	v_mul_f32_e32 v1, v2, v1
	v_fma_f32 v2, v1, s0, -v0
	v_cndmask_b32_e32 v3, v211, v252, vcc
	v_lshlrev_b32_e32 v228, 2, v3
	ds_bpermute_b32 v3, v228, v2
	v_cmp_lt_i32_e32 vcc, v253, v213
	s_waitcnt lgkmcnt(0)
	v_max_f32_e32 v3, v3, v3
	v_max_f32_e32 v2, v2, v3
	v_cndmask_b32_e32 v3, v211, v253, vcc
	v_lshlrev_b32_e32 v227, 2, v3
	ds_bpermute_b32 v3, v227, v2
	v_cmp_lt_i32_e32 vcc, v254, v213
	s_waitcnt lgkmcnt(0)
	v_max_f32_e32 v3, v3, v3
	v_max_f32_e32 v2, v2, v3
	v_cndmask_b32_e32 v3, v211, v254, vcc
	v_lshlrev_b32_e32 v226, 2, v3
	ds_bpermute_b32 v3, v226, v2
	v_cmp_lt_i32_e32 vcc, v212, v213
	s_waitcnt lgkmcnt(0)
	v_max_f32_e32 v3, v3, v3
	v_max_f32_e32 v2, v2, v3
	v_cndmask_b32_e32 v3, v211, v212, vcc
	v_lshlrev_b32_e32 v225, 2, v3
	ds_bpermute_b32 v3, v225, v2
	v_cmp_lt_i32_e32 vcc, v218, v213
	s_waitcnt lgkmcnt(0)
	v_max_f32_e32 v3, v3, v3
	v_max_f32_e32 v2, v2, v3
	v_cndmask_b32_e32 v3, v211, v218, vcc
	v_lshlrev_b32_e32 v224, 2, v3
	ds_bpermute_b32 v3, v224, v2
	v_cmp_eq_u32_e32 vcc, 0, v33
	s_and_saveexec_b64 s[0:1], vcc
	s_cbranch_execz .LBB0_309
	s_waitcnt lgkmcnt(0)
	v_max_f32_e32 v3, v3, v3
	v_max_f32_e32 v2, v2, v2
	v_max_f32_e32 v2, v2, v3
	v_lshl_add_u32 v3, v21, 2, 0
	v_add_u32_e32 v3, 0x10000, v3
	ds_write_b32 v3, v2
